# 5120 layer-1 expert-weight transposes tiles moved from P0b into layer 0's in-proj phase, done by the 216 blocks that have no third in-proj tile
# speedup vs baseline: 1.0010x; 1.0010x over previous
; #define LAUNDER(v) asm volatile("" : "+s"(v))
; __device__ __forceinline__ int vtid() { int t = threadIdx.x; asm volatile("" : "+v"(t)); return t; }
; __global__ void __launch_bounds__(256, 2) fwd_megakernel(Params p) {
;   cg::grid_group grid = cg::this_grid();
;   __shared__ __attribute__((aligned(16))) char smem[65536 - 64];
;   __shared__ int s_job;
;   __shared__ uint4 xb_words;
;   const int tid = vtid();
;   const int nb = gridDim.x, bid = blockIdx.x;
;   char* ws = p.ws;
;   LAUNDER(ws);
;   if (p.out == nullptr) grid.sync();
_Z14fwd_megakernel6Params:
	v_writelane_b32 v236, s0, 62
	v_writelane_b32 v236, s1, 63
	s_add_u32 s4, s0, 0xf0
	v_writelane_b32 v239, s2, 0
	s_load_dword s33, s[0:1], 0xf8
	s_load_dwordx4 s[64:67], s[0:1], 0xe0
	s_load_dwordx2 s[2:3], s[0:1], 0xf0
	s_addc_u32 s5, s1, 0
	v_and_b32_e32 v172, 0x3ff, v0
	v_mov_b32_e32 v148, v172
	s_waitcnt lgkmcnt(0)
	s_mov_b64 s[36:37], s[66:67]
	v_writelane_b32 v239, s2, 1
	s_cmp_lg_u64 s[64:65], 0
	s_nop 0
	v_writelane_b32 v239, s3, 2
	s_movk_i32 s2, 0x3ff
	s_cbranch_scc1 .LBB0_12
	v_lshrrev_b32_e32 v1, 20, v0
	v_lshrrev_b32_e32 v0, 10, v0
	v_or_b32_e32 v0, v0, v1
	v_and_or_b32 v0, v0, s2, v172
	v_cmp_eq_u32_e32 vcc, 0, v0
	s_barrier
	s_and_saveexec_b64 s[2:3], vcc
	s_cbranch_execz .LBB0_11
	buffer_wbl2 sc1
	s_load_dwordx2 s[4:5], s[4:5], 0x58
	v_mov_b32_e32 v2, 0
	s_mov_b64 s[6:7], exec
	v_mbcnt_lo_u32_b32 v1, s6, 0
	v_mbcnt_hi_u32_b32 v1, s7, v1
	s_waitcnt lgkmcnt(0)
	global_load_dword v0, v2, s[4:5] offset:40
	v_cmp_eq_u32_e32 vcc, 0, v1
	s_and_saveexec_b64 s[8:9], vcc
	s_cbranch_execz .LBB0_4
	s_bcnt1_i32_b64 s6, s[6:7]
	v_mov_b32_e32 v3, s6
	global_atomic_add v3, v2, v3, s[4:5] offset:32 sc0

; __device__ __forceinline__ TrJob tr_decode(const Params& p, char* ws, int job) {
;   TrJob t;
;   int l = job / TJ_PER_LAYER, rj = job % TJ_PER_LAYER;
;   if (rj < 640) {
;     t.src = p.w_in + (size_t)l * 1024 * 2560; t.K = 1024; t.N = 2560; t.kt = rj / 40; t.nt = rj % 40;
;     t.dst = (u16*)(ws + OFF_WINT) + (size_t)l * 2560 * 1024; t.mode = 0;
;   } else if (rj < 896) {
;     rj -= 640;
;     t.src = p.w_out + (size_t)l * 1024 * 1024; t.K = 1024; t.N = 1024; t.kt = rj / 16; t.nt = rj % 16;
;     t.dst = (u16*)(ws + OFF_WOUTT) + (size_t)l * 1024 * 1024; t.mode = 0;
;   } else {
;     rj -= 896;
;     int e = rj / 1536, q = rj % 1536;
;     size_t eo = (size_t)(l * 16 + e);
;     if (q < 512) {
;       t.src = p.w_gate + eo * 1024 * 2048; t.K = 1024; t.N = 2048; t.kt = q / 32; t.nt = q % 32;
;       t.dst = (u16*)(ws + OFF_WGUT) + eo * 4096 * 1024; t.mode = 1;
;     } else if (q < 1024) {
;       q -= 512;
;       t.src = p.w_up + eo * 1024 * 2048; t.K = 1024; t.N = 2048; t.kt = q / 32; t.nt = q % 32;
;       t.dst = (u16*)(ws + OFF_WGUT) + eo * 4096 * 1024; t.mode = 2;
;     } else {
;       q -= 1024;
;       t.src = p.w_down + eo * 2048 * 1024; t.K = 2048; t.N = 1024; t.kt = q / 16; t.nt = q % 16;
;       t.dst = (u16*)(ws + OFF_WDT) + eo * 1024 * 2048; t.mode = 0;
;     }
; __device__ __forceinline__ void p0_transposes(const Params& p, char* smem, int bid, int nb, int jlo, int jhi) {
;     ...
;   int j = jlo + bid * 2;
;   if (j < jhi) { tr_load(p, ws, j, tid, c0); tr_load(p, ws, j + 1, tid, c1); }
;   for (; j < jhi; j += 2 * nb) {
;     const int jn = j + 2 * nb;
;     if (jn < jhi) { tr_load(p, ws, jn, tid, n0); tr_load(p, ws, jn + 1, tid, n1); }
.LBB0_174:
	s_add_i32 s96, s97, s75
	s_cmp_gt_i32 s96, 0x8aff
	s_cselect_b64 s[0:1], -1, 0
	s_and_b64 vcc, exec, s[0:1]
	s_cbranch_vccnz .LBB0_208
	s_mul_hi_i32 s10, s96, 0x5254e78f
	s_lshr_b32 s11, s10, 31
	s_ashr_i32 s10, s10, 13
	s_add_i32 s52, s10, s11
	s_mul_i32 s10, s52, 0xffff9c80
	s_add_i32 s10, s96, s10
	s_cmpk_gt_i32 s10, 0x27f
	s_mov_b64 s[58:59], -1
	s_cbranch_scc0 .LBB0_189
	s_cmpk_gt_u32 s10, 0x37f
	s_cbranch_scc0 .LBB0_186
	s_add_i32 s11, s10, 0xfc80
	s_and_b32 s33, s11, 0xffff
	s_mul_i32 s33, s33, 0xaaab
	s_lshr_b32 s33, s33, 26
	s_mul_i32 s40, s33, 0x600
	s_sub_i32 s11, s11, s40
	s_and_b32 s40, s11, 0xffff
	s_lshl_b32 s11, s52, 4
	s_add_i32 s54, s11, s33
	s_ashr_i32 s55, s54, 31
	s_lshl_b64 s[58:59], s[54:55], 23
	s_cmpk_gt_u32 s40, 0x1ff
	s_mov_b64 s[60:61], -1
	s_cbranch_scc0 .LBB0_183
	s_cmpk_gt_u32 s40, 0x3ff
	s_mov_b64 s[56:57], -1
	s_cbranch_scc0 .LBB0_180
	v_readlane_b32 s12, v238, 25
	s_add_i32 s11, s40, 0xfffffc00
	v_readlane_b32 s18, v238, 31
	v_readlane_b32 s19, v238, 32
	s_add_u32 s54, s18, s58
	v_readlane_b32 s13, v238, 26
	v_readlane_b32 s14, v238, 27
	v_readlane_b32 s15, v238, 28
	v_readlane_b32 s16, v238, 29
	v_readlane_b32 s17, v238, 30
	s_addc_u32 s55, s19, s59
	s_lshr_b32 s33, s11, 4
	s_and_b32 s11, s40, 15
	s_mov_b64 s[56:57], 0

; __device__ __forceinline__ TrJob tr_decode(const Params& p, char* ws, int job) {
;   TrJob t;
;   int l = job / TJ_PER_LAYER, rj = job % TJ_PER_LAYER;
;   if (rj < 640) {
;     t.src = p.w_in + (size_t)l * 1024 * 2560; t.K = 1024; t.N = 2560; t.kt = rj / 40; t.nt = rj % 40;
;     t.dst = (u16*)(ws + OFF_WINT) + (size_t)l * 2560 * 1024; t.mode = 0;
;   } else if (rj < 896) {
;     rj -= 640;
;     t.src = p.w_out + (size_t)l * 1024 * 1024; t.K = 1024; t.N = 1024; t.kt = rj / 16; t.nt = rj % 16;
;     t.dst = (u16*)(ws + OFF_WOUTT) + (size_t)l * 1024 * 1024; t.mode = 0;
;   } else {
;     rj -= 896;
;     int e = rj / 1536, q = rj % 1536;
;     size_t eo = (size_t)(l * 16 + e);
;     if (q < 512) {
;       t.src = p.w_gate + eo * 1024 * 2048; t.K = 1024; t.N = 2048; t.kt = q / 32; t.nt = q % 32;
;       t.dst = (u16*)(ws + OFF_WGUT) + eo * 4096 * 1024; t.mode = 1;
;     } else if (q < 1024) {
;       q -= 512;
;       t.src = p.w_up + eo * 1024 * 2048; t.K = 1024; t.N = 2048; t.kt = q / 32; t.nt = q % 32;
;       t.dst = (u16*)(ws + OFF_WGUT) + eo * 4096 * 1024; t.mode = 2;
;     } else {
;       q -= 1024;
;       t.src = p.w_down + eo * 2048 * 1024; t.K = 2048; t.N = 1024; t.kt = q / 16; t.nt = q % 16;
;       t.dst = (u16*)(ws + OFF_WDT) + eo * 1024 * 2048; t.mode = 0;
;     }
;   }
;   return t;
; }
; __device__ __forceinline__ void tr_load(const Params& p, char* ws, int job, int tid, float4 (&r)[4]) {
;   TrJob t = tr_decode(p, ws, job);
;   const int c4 = tid & 15, rr = tid >> 4;
;   const float* s0 = t.src + (size_t)(t.kt * 64 + rr) * t.N + t.nt * 64 + c4 * 4;
; #pragma unroll
;   for (int pp = 0; pp < 4; ++pp) {
;     f32x4 v_ = __builtin_nontemporal_load((const f32x4*)(s0 + (size_t)(16 * pp) * t.N));
;     r[pp] = make_float4(v_[0], v_[1], v_[2], v_[3]);
;   }
; }
.Ltrp1_check:
	v_readlane_b32 s0, v237, 29
	s_cmp_lg_u32 s0, 0
	s_cbranch_scc0 .LBB0_631
	v_readlane_b32 s0, v239, 0
	s_cmpk_lt_i32 s0, 296
	s_cbranch_scc1 .LBB0_631
	v_readlane_b32 s100, v236, 62
	v_readlane_b32 s101, v236, 63
	v_writelane_b32 v255, s64, 0
	v_writelane_b32 v255, s65, 1
	v_writelane_b32 v255, s66, 2
	v_writelane_b32 v255, s67, 3
	v_writelane_b32 v255, s68, 4
	v_writelane_b32 v255, s69, 5
	v_writelane_b32 v255, s70, 6
	v_writelane_b32 v255, s71, 7
	v_writelane_b32 v255, s72, 8
	v_writelane_b32 v255, s73, 9
	v_writelane_b32 v255, s74, 10
	v_writelane_b32 v255, s75, 11
	v_writelane_b32 v255, s76, 12
	v_writelane_b32 v255, s77, 13
	v_writelane_b32 v255, s78, 14
	v_writelane_b32 v255, s79, 15
	v_writelane_b32 v255, s80, 16
	v_writelane_b32 v255, s81, 17
	v_writelane_b32 v255, s82, 18
	v_writelane_b32 v255, s83, 19
	v_writelane_b32 v255, s84, 20
	v_writelane_b32 v255, s85, 21
	v_writelane_b32 v255, s86, 22
	v_writelane_b32 v255, s87, 23
	v_writelane_b32 v255, s88, 24
	v_writelane_b32 v255, s89, 25
	v_writelane_b32 v255, s90, 26
	v_writelane_b32 v255, s91, 27
	v_writelane_b32 v255, s92, 28
	v_writelane_b32 v255, s93, 29
	v_writelane_b32 v255, s94, 30
	v_writelane_b32 v255, s95, 31
	v_writelane_b32 v255, s96, 32
	v_writelane_b32 v255, s97, 33
	v_writelane_b32 v255, s98, 34
	v_writelane_b32 v255, s99, 35
	v_writelane_b32 v255, vcc_lo, 36
	v_writelane_b32 v255, vcc_hi, 37
	s_load_dwordx4 s[64:67], s[100:101], 0x40
	s_load_dwordx4 s[68:71], s[100:101], 0xc8
	s_load_dwordx2 s[72:73], s[100:101], 0xd8
	s_load_dwordx2 s[74:75], s[100:101], 0xe8
	v_and_b32_e32 v241, 15, v172
	v_lshrrev_b32_e32 v242, 4, v172
	v_lshlrev_b32_e32 v241, 4, v241
	v_mul_u32_u24_e32 v243, 0x104, v242
	v_add_u32_e32 v243, v243, v241
	v_and_b32_e32 v246, 7, v172
	v_lshrrev_b32_e32 v245, 3, v172
	v_mul_u32_u24_e32 v244, 0x820, v246
	v_lshl_add_u32 v244, v245, 2, v244
	v_lshlrev_b32_e32 v246, 4, v246
	v_readlane_b32 s76, v239, 0
	s_add_u32 s76, s76, 35288
	s_movk_i32 s77, 12
	s_mov_b32 s96, 0
	s_waitcnt lgkmcnt(0)
.Ltrp1_batch:
	s_min_u32 s78, s76, 40703
	s_cmp_ge_u32 s78, 25472
	s_cselect_b32 s79, 1, 0
	s_cselect_b32 s85, 25472, 0
	s_sub_u32 s78, s78, s85
	s_cmp_lt_u32 s78, 640
	s_cbranch_scc0 .Ltr_p1l0_notin
	s_mul_hi_u32 s80, s78, 107374183
	s_mul_i32 s85, s80, 40
	s_sub_u32 s81, s78, s85
	s_movk_i32 s82, 2560
	s_movk_i32 s83, 1024
	s_mov_b32 s84, -1
	s_mul_i32 s85, s79, 10485760
	s_add_u32 s86, s64, s85
	s_addc_u32 s87, s65, 0
	s_mul_i32 s85, s79, 5242880
	s_add_u32 s88, s74, s85
	s_addc_u32 s89, s75, 0
	s_branch .Ltr_p1l0_dec_done
.Ltr_p1l0_notin:
	s_cmp_lt_u32 s78, 896
	s_cbranch_scc0 .Ltr_p1l0_expert
	s_sub_u32 s78, s78, 640
	s_lshr_b32 s80, s78, 4
	s_and_b32 s81, s78, 15
	s_movk_i32 s82, 1024
	s_movk_i32 s83, 1024
	s_mov_b32 s84, -1
	s_mul_i32 s85, s79, 4194304
	s_add_u32 s86, s66, s85
	s_addc_u32 s87, s67, 0
	s_mul_i32 s85, s79, 2097152
	s_add_u32 s85, s85, 0xa00000
	s_add_u32 s88, s74, s85
	s_addc_u32 s89, s75, 0
	s_branch .Ltr_p1l0_dec_done
.Ltr_p1l0_expert:
	s_sub_u32 s78, s78, 896
	s_lshr_b32 s85, s78, 9
	s_mul_hi_u32 s85, s85, 0x55555556
	s_mul_i32 s80, s85, 1536
	s_sub_u32 s78, s78, s80
	s_lshl_b32 s79, s79, 4
	s_add_u32 s79, s79, s85
	s_cmp_lt_u32 s78, 1024
	s_cbranch_scc0 .Ltr_p1l0_down
	s_cmp_lt_u32 s78, 512
	s_cselect_b32 s84, 0, 32
	s_cselect_b32 s86, s68, s70
	s_cselect_b32 s87, s69, s71
	s_and_b32 s78, s78, 511
	s_lshr_b32 s80, s78, 5
	s_and_b32 s81, s78, 31
	s_movk_i32 s82, 2048
	s_movk_i32 s83, 1024
	s_lshl_b32 s85, s79, 23
	s_add_u32 s86, s86, s85
	s_addc_u32 s87, s87, 0
	s_add_u32 s85, s85, 0xe00000
	s_add_u32 s88, s74, s85
	s_addc_u32 s89, s75, 0
	s_branch .Ltr_p1l0_dec_done
.Ltr_p1l0_down:
	s_sub_u32 s78, s78, 1024
	s_lshr_b32 s80, s78, 4
	s_and_b32 s81, s78, 15
	s_movk_i32 s82, 1024
	s_movk_i32 s83, 2048
	s_mov_b32 s84, -1
	s_lshl_b32 s85, s79, 23
	s_add_u32 s86, s72, s85
	s_addc_u32 s87, s73, 0
	s_lshl_b32 s85, s79, 22
	s_add_u32 s85, s85, 0x10e00000
	s_add_u32 s88, s74, s85
	s_addc_u32 s89, s75, 0
.Ltr_p1l0_dec_done:
	s_mul_i32 s85, s80, s82
	s_lshl_b32 s85, s85, 8
	s_lshl_b32 s79, s81, 8
	s_add_u32 s85, s85, s79
	s_add_u32 s90, s86, s85
	s_addc_u32 s91, s87, 0
	s_lshl_b32 s92, s82, 2
	s_lshl_b32 s93, s82, 6
	v_mad_u32_u24 v240, v242, s92, v241
	global_load_dwordx4 v[212:215], v240, s[90:91] nt
	v_add_u32_e32 v211, s93, v240
	global_load_dwordx4 v[216:219], v211, s[90:91] nt
	v_add_u32_e32 v240, s93, v211
	global_load_dwordx4 v[220:223], v240, s[90:91] nt
	v_add_u32_e32 v211, s93, v240
	global_load_dwordx4 v[224:227], v211, s[90:91] nt
	s_add_u32 s76, s76, 216
	s_min_u32 s78, s76, 40703
	s_cmp_ge_u32 s78, 25472
	s_cselect_b32 s79, 1, 0
	s_cselect_b32 s85, 25472, 0
	s_sub_u32 s78, s78, s85
	s_cmp_lt_u32 s78, 640
	s_cbranch_scc0 .Ltr_p1l1_notin
	s_mul_hi_u32 s80, s78, 107374183
	s_mul_i32 s85, s80, 40
	s_sub_u32 s81, s78, s85
	s_movk_i32 s82, 2560
	s_movk_i32 s83, 1024
	s_mov_b32 s84, -1
	s_mul_i32 s85, s79, 10485760
	s_add_u32 s86, s64, s85
	s_addc_u32 s87, s65, 0
	s_mul_i32 s85, s79, 5242880
	s_add_u32 s88, s74, s85
	s_addc_u32 s89, s75, 0
	s_branch .Ltr_p1l1_dec_done

; __device__ __forceinline__ void tr_load(const Params& p, char* ws, int job, int tid, float4 (&r)[4]) {
;   TrJob t = tr_decode(p, ws, job);
;   const int c4 = tid & 15, rr = tid >> 4;
;   const float* s0 = t.src + (size_t)(t.kt * 64 + rr) * t.N + t.nt * 64 + c4 * 4;
; #pragma unroll
;   for (int pp = 0; pp < 4; ++pp) {
;     f32x4 v_ = __builtin_nontemporal_load((const f32x4*)(s0 + (size_t)(16 * pp) * t.N));
;     r[pp] = make_float4(v_[0], v_[1], v_[2], v_[3]);
;   }
; }
; __device__ __forceinline__ void tr_lds_write(float* tile, int tid, const float4 (&r)[4]) {
;   const int c4 = tid & 15, rr = tid >> 4;
; #pragma unroll
;   for (int pp = 0; pp < 4; ++pp) {
;     float* t = &tile[(rr + 16 * pp) * 65 + c4 * 4];
;     t[0] = r[pp].x; t[1] = r[pp].y; t[2] = r[pp].z; t[3] = r[pp].w;
;   }
; }
; __device__ __forceinline__ void tr_store(const Params& p, char* ws, int job, int tid, const float* tile) {
;   TrJob t = tr_decode(p, ws, job);
;   const int kc = tid & 7, nn = tid >> 3;
; #pragma unroll
;   for (int pp = 0; pp < 2; ++pp) {
;     int n = nn + 32 * pp;
;     float v[8];
; #pragma unroll
;     for (int j = 0; j < 8; ++j) v[j] = tile[(kc * 8 + j) * 65 + n];
.Ltr_p1l1_dec_done:
	s_mul_i32 s85, s80, s82
	s_lshl_b32 s85, s85, 8
	s_lshl_b32 s79, s81, 8
	s_add_u32 s85, s85, s79
	s_add_u32 s90, s86, s85
	s_addc_u32 s91, s87, 0
	s_lshl_b32 s92, s82, 2
	s_lshl_b32 s93, s82, 6
	v_mad_u32_u24 v240, v242, s92, v241
	global_load_dwordx4 v[228:231], v240, s[90:91] nt
	v_add_u32_e32 v211, s93, v240
	global_load_dwordx4 v[232:235], v211, s[90:91] nt
	v_add_u32_e32 v240, s93, v211
	global_load_dwordx4 v[186:189], v240, s[90:91] nt
	v_add_u32_e32 v211, s93, v240
	global_load_dwordx4 v[190:193], v211, s[90:91] nt
	s_add_u32 s76, s76, 216
	s_sub_u32 s76, s76, 432
	s_waitcnt vmcnt(0)
	v_add_u32_e32 v247, s96, v243
	ds_write_b32 v247, v212 offset:0
	ds_write_b32 v247, v213 offset:4
	ds_write_b32 v247, v214 offset:8
	ds_write_b32 v247, v215 offset:12
	ds_write_b32 v247, v216 offset:4160
	ds_write_b32 v247, v217 offset:4164
	ds_write_b32 v247, v218 offset:4168
	ds_write_b32 v247, v219 offset:4172
	ds_write_b32 v247, v220 offset:8320
	ds_write_b32 v247, v221 offset:8324
	ds_write_b32 v247, v222 offset:8328
	ds_write_b32 v247, v223 offset:8332
	ds_write_b32 v247, v224 offset:12480
	ds_write_b32 v247, v225 offset:12484
	ds_write_b32 v247, v226 offset:12488
	ds_write_b32 v247, v227 offset:12492
	v_add_u32_e32 v247, s96, v244
	s_waitcnt lgkmcnt(0)
	s_barrier
	ds_read_b32 v212, v247 offset:0
	ds_read_b32 v213, v247 offset:260
	ds_read_b32 v214, v247 offset:520
	ds_read_b32 v215, v247 offset:780
	ds_read_b32 v216, v247 offset:1040
	ds_read_b32 v217, v247 offset:1300
	ds_read_b32 v218, v247 offset:1560
	ds_read_b32 v219, v247 offset:1820
	ds_read_b32 v220, v247 offset:128
	ds_read_b32 v221, v247 offset:388
	ds_read_b32 v222, v247 offset:648
	ds_read_b32 v223, v247 offset:908
	ds_read_b32 v224, v247 offset:1168
	ds_read_b32 v225, v247 offset:1428
	ds_read_b32 v226, v247 offset:1688
	ds_read_b32 v227, v247 offset:1948
	s_min_u32 s78, s76, 40703
	s_cmp_ge_u32 s78, 25472
	s_cselect_b32 s79, 1, 0
	s_cselect_b32 s85, 25472, 0
	s_sub_u32 s78, s78, s85
	s_cmp_lt_u32 s78, 640
	s_cbranch_scc0 .Ltr_p1s0_notin
	s_mul_hi_u32 s80, s78, 107374183
	s_mul_i32 s85, s80, 40
	s_sub_u32 s81, s78, s85
	s_movk_i32 s82, 2560
	s_movk_i32 s83, 1024
	s_mov_b32 s84, -1
	s_mul_i32 s85, s79, 10485760
	s_add_u32 s86, s64, s85
	s_addc_u32 s87, s65, 0
	s_mul_i32 s85, s79, 5242880
	s_add_u32 s88, s74, s85
	s_addc_u32 s89, s75, 0
	s_branch .Ltr_p1s0_dec_done

; __device__ __forceinline__ unsigned pack2(float a, float b) { return (unsigned)f2bf(a) | ((unsigned)f2bf(b) << 16); }
; __device__ __forceinline__ void tr_store(const Params& p, char* ws, int job, int tid, const float* tile) {
;   TrJob t = tr_decode(p, ws, job);
;   const int kc = tid & 7, nn = tid >> 3;
; #pragma unroll
;   for (int pp = 0; pp < 2; ++pp) {
;     int n = nn + 32 * pp;
;     float v[8];
; #pragma unroll
;     for (int j = 0; j < 8; ++j) v[j] = tile[(kc * 8 + j) * 65 + n];
;     uint4 o;
;     o.x = pack2(v[0], v[1]); o.y = pack2(v[2], v[3]); o.z = pack2(v[4], v[5]); o.w = pack2(v[6], v[7]);
;     int gn = t.nt * 64 + n;
;     int drow = t.mode == 0 ? gn : gu_row(t.mode - 1, gn);
;     *(uint4*)&t.dst[(size_t)drow * t.K + t.kt * 64 + kc * 8] = o;
;   }
; }
.Ltr_p1s0_dec_done:
	s_lshl_b32 s97, s83, 1
	s_cmp_eq_u32 s84, -1
	s_cselect_b32 s79, 6, 7
	s_cselect_b32 s85, 32, 64
	s_cselect_b32 s78, 0, s84
	s_lshl_b32 s79, s81, s79
	s_add_u32 s79, s79, s78
	s_add_u32 s85, s85, s79
	s_mul_i32 s79, s79, s97
	s_mul_i32 s85, s85, s97
	s_lshl_b32 s78, s80, 7
	s_add_u32 s79, s79, s78
	s_add_u32 s85, s85, s78
	s_add_u32 s94, s88, s79
	s_addc_u32 s95, s89, 0
	s_add_u32 s98, s88, s85
	s_addc_u32 s99, s89, 0
	v_mad_u32_u24 v254, v245, s97, v246
	s_movk_i32 s78, 0x7fff
	s_mov_b32 s79, 0xffff0000
	s_waitcnt lgkmcnt(0)
	v_bfe_u32 v252, v212, 16, 1
	v_bfe_u32 v253, v213, 16, 1
	v_add3_u32 v252, v212, v252, s78
	v_add3_u32 v253, v213, v253, s78
	v_lshrrev_b32_e32 v252, 16, v252
	v_and_or_b32 v248, v253, s79, v252
	v_bfe_u32 v252, v214, 16, 1
	v_bfe_u32 v253, v215, 16, 1
	v_add3_u32 v252, v214, v252, s78
	v_add3_u32 v253, v215, v253, s78
	v_lshrrev_b32_e32 v252, 16, v252
	v_and_or_b32 v249, v253, s79, v252
	v_bfe_u32 v252, v216, 16, 1
	v_bfe_u32 v253, v217, 16, 1
	v_add3_u32 v252, v216, v252, s78
	v_add3_u32 v253, v217, v253, s78
	v_lshrrev_b32_e32 v252, 16, v252
	v_and_or_b32 v250, v253, s79, v252
	v_bfe_u32 v252, v218, 16, 1
	v_bfe_u32 v253, v219, 16, 1
	v_add3_u32 v252, v218, v252, s78
	v_add3_u32 v253, v219, v253, s78
	v_lshrrev_b32_e32 v252, 16, v252
	v_and_or_b32 v251, v253, s79, v252
	global_store_dwordx4 v254, v[248:251], s[94:95]
	s_nop 1
	v_bfe_u32 v252, v220, 16, 1
	v_bfe_u32 v253, v221, 16, 1
	v_add3_u32 v252, v220, v252, s78
	v_add3_u32 v253, v221, v253, s78
	v_lshrrev_b32_e32 v252, 16, v252
	v_and_or_b32 v248, v253, s79, v252
	v_bfe_u32 v252, v222, 16, 1
	v_bfe_u32 v253, v223, 16, 1
	v_add3_u32 v252, v222, v252, s78
	v_add3_u32 v253, v223, v253, s78
	v_lshrrev_b32_e32 v252, 16, v252
	v_and_or_b32 v249, v253, s79, v252
	v_bfe_u32 v252, v224, 16, 1
	v_bfe_u32 v253, v225, 16, 1
	v_add3_u32 v252, v224, v252, s78
	v_add3_u32 v253, v225, v253, s78
	v_lshrrev_b32_e32 v252, 16, v252
	v_and_or_b32 v250, v253, s79, v252
	v_bfe_u32 v252, v226, 16, 1
	v_bfe_u32 v253, v227, 16, 1
	v_add3_u32 v252, v226, v252, s78
	v_add3_u32 v253, v227, v253, s78
	v_lshrrev_b32_e32 v252, 16, v252
	v_and_or_b32 v251, v253, s79, v252
	global_store_dwordx4 v254, v[248:251], s[98:99]
	s_xor_b32 s96, s96, 0x4100
	s_add_u32 s76, s76, 216
	v_add_u32_e32 v247, s96, v243
	ds_write_b32 v247, v228 offset:0
	ds_write_b32 v247, v229 offset:4
	ds_write_b32 v247, v230 offset:8
	ds_write_b32 v247, v231 offset:12
	ds_write_b32 v247, v232 offset:4160
	ds_write_b32 v247, v233 offset:4164
	ds_write_b32 v247, v234 offset:4168
	ds_write_b32 v247, v235 offset:4172
	ds_write_b32 v247, v186 offset:8320
	ds_write_b32 v247, v187 offset:8324
	ds_write_b32 v247, v188 offset:8328
	ds_write_b32 v247, v189 offset:8332
	ds_write_b32 v247, v190 offset:12480
	ds_write_b32 v247, v191 offset:12484
	ds_write_b32 v247, v192 offset:12488
	ds_write_b32 v247, v193 offset:12492
	v_add_u32_e32 v247, s96, v244
	s_waitcnt lgkmcnt(0)
	s_barrier
	ds_read_b32 v228, v247 offset:0
	ds_read_b32 v229, v247 offset:260
	ds_read_b32 v230, v247 offset:520
	ds_read_b32 v231, v247 offset:780
	ds_read_b32 v232, v247 offset:1040
	ds_read_b32 v233, v247 offset:1300
	ds_read_b32 v234, v247 offset:1560
	ds_read_b32 v235, v247 offset:1820
	ds_read_b32 v186, v247 offset:128
	ds_read_b32 v187, v247 offset:388
	ds_read_b32 v188, v247 offset:648
	ds_read_b32 v189, v247 offset:908
	ds_read_b32 v190, v247 offset:1168
	ds_read_b32 v191, v247 offset:1428
	ds_read_b32 v192, v247 offset:1688
	ds_read_b32 v193, v247 offset:1948
	s_min_u32 s78, s76, 40703
	s_cmp_ge_u32 s78, 25472
	s_cselect_b32 s79, 1, 0
	s_cselect_b32 s85, 25472, 0
	s_sub_u32 s78, s78, s85
	s_cmp_lt_u32 s78, 640
	s_cbranch_scc0 .Ltr_p1s1_notin
	s_mul_hi_u32 s80, s78, 107374183
	s_mul_i32 s85, s80, 40
	s_sub_u32 s81, s78, s85
	s_movk_i32 s82, 2560
	s_movk_i32 s83, 1024
	s_mov_b32 s84, -1
	s_mul_i32 s85, s79, 10485760
	s_add_u32 s86, s64, s85
	s_addc_u32 s87, s65, 0
	s_mul_i32 s85, s79, 5242880
	s_add_u32 s88, s74, s85
	s_addc_u32 s89, s75, 0
	s_branch .Ltr_p1s1_dec_done

; __device__ __forceinline__ unsigned pack2(float a, float b) { return (unsigned)f2bf(a) | ((unsigned)f2bf(b) << 16); }
; __device__ __forceinline__ void tr_store(const Params& p, char* ws, int job, int tid, const float* tile) {
;   TrJob t = tr_decode(p, ws, job);
;   const int kc = tid & 7, nn = tid >> 3;
; #pragma unroll
;   for (int pp = 0; pp < 2; ++pp) {
;     int n = nn + 32 * pp;
;     float v[8];
; #pragma unroll
;     for (int j = 0; j < 8; ++j) v[j] = tile[(kc * 8 + j) * 65 + n];
;     uint4 o;
;     o.x = pack2(v[0], v[1]); o.y = pack2(v[2], v[3]); o.z = pack2(v[4], v[5]); o.w = pack2(v[6], v[7]);
;     int gn = t.nt * 64 + n;
;     int drow = t.mode == 0 ? gn : gu_row(t.mode - 1, gn);
;     *(uint4*)&t.dst[(size_t)drow * t.K + t.kt * 64 + kc * 8] = o;
;   }
; }
; __device__ __forceinline__ void p0_transposes(const Params& p, char* smem, int bid, int nb, int jlo, int jhi) {
;     ...
;     tr_store(p, ws, j + 1, tid, tileB);
;     __syncthreads();
; #pragma unroll
;     for (int q = 0; q < 4; ++q) { c0[q] = n0[q]; c1[q] = n1[q]; }
;   }
.Ltr_p1s1_dec_done:
	s_lshl_b32 s97, s83, 1
	s_cmp_eq_u32 s84, -1
	s_cselect_b32 s79, 6, 7
	s_cselect_b32 s85, 32, 64
	s_cselect_b32 s78, 0, s84
	s_lshl_b32 s79, s81, s79
	s_add_u32 s79, s79, s78
	s_add_u32 s85, s85, s79
	s_mul_i32 s79, s79, s97
	s_mul_i32 s85, s85, s97
	s_lshl_b32 s78, s80, 7
	s_add_u32 s79, s79, s78
	s_add_u32 s85, s85, s78
	s_add_u32 s94, s88, s79
	s_addc_u32 s95, s89, 0
	s_add_u32 s98, s88, s85
	s_addc_u32 s99, s89, 0
	v_mad_u32_u24 v254, v245, s97, v246
	s_movk_i32 s78, 0x7fff
	s_mov_b32 s79, 0xffff0000
	s_waitcnt lgkmcnt(0)
	v_bfe_u32 v252, v228, 16, 1
	v_bfe_u32 v253, v229, 16, 1
	v_add3_u32 v252, v228, v252, s78
	v_add3_u32 v253, v229, v253, s78
	v_lshrrev_b32_e32 v252, 16, v252
	v_and_or_b32 v248, v253, s79, v252
	v_bfe_u32 v252, v230, 16, 1
	v_bfe_u32 v253, v231, 16, 1
	v_add3_u32 v252, v230, v252, s78
	v_add3_u32 v253, v231, v253, s78
	v_lshrrev_b32_e32 v252, 16, v252
	v_and_or_b32 v249, v253, s79, v252
	v_bfe_u32 v252, v232, 16, 1
	v_bfe_u32 v253, v233, 16, 1
	v_add3_u32 v252, v232, v252, s78
	v_add3_u32 v253, v233, v253, s78
	v_lshrrev_b32_e32 v252, 16, v252
	v_and_or_b32 v250, v253, s79, v252
	v_bfe_u32 v252, v234, 16, 1
	v_bfe_u32 v253, v235, 16, 1
	v_add3_u32 v252, v234, v252, s78
	v_add3_u32 v253, v235, v253, s78
	v_lshrrev_b32_e32 v252, 16, v252
	v_and_or_b32 v251, v253, s79, v252
	global_store_dwordx4 v254, v[248:251], s[94:95]
	s_nop 1
	v_bfe_u32 v252, v186, 16, 1
	v_bfe_u32 v253, v187, 16, 1
	v_add3_u32 v252, v186, v252, s78
	v_add3_u32 v253, v187, v253, s78
	v_lshrrev_b32_e32 v252, 16, v252
	v_and_or_b32 v248, v253, s79, v252
	v_bfe_u32 v252, v188, 16, 1
	v_bfe_u32 v253, v189, 16, 1
	v_add3_u32 v252, v188, v252, s78
	v_add3_u32 v253, v189, v253, s78
	v_lshrrev_b32_e32 v252, 16, v252
	v_and_or_b32 v249, v253, s79, v252
	v_bfe_u32 v252, v190, 16, 1
	v_bfe_u32 v253, v191, 16, 1
	v_add3_u32 v252, v190, v252, s78
	v_add3_u32 v253, v191, v253, s78
	v_lshrrev_b32_e32 v252, 16, v252
	v_and_or_b32 v250, v253, s79, v252
	v_bfe_u32 v252, v192, 16, 1
	v_bfe_u32 v253, v193, 16, 1
	v_add3_u32 v252, v192, v252, s78
	v_add3_u32 v253, v193, v253, s78
	v_lshrrev_b32_e32 v252, 16, v252
	v_and_or_b32 v251, v253, s79, v252
	global_store_dwordx4 v254, v[248:251], s[98:99]
	s_xor_b32 s96, s96, 0x4100
	s_add_u32 s76, s76, 216
	s_sub_u32 s77, s77, 1
	s_cmp_lg_u32 s77, 0
	s_cbranch_scc1 .Ltrp1_batch
	s_waitcnt vmcnt(0) lgkmcnt(0)
	s_barrier
	v_readlane_b32 s64, v255, 0
	v_readlane_b32 s65, v255, 1
	v_readlane_b32 s66, v255, 2
	v_readlane_b32 s67, v255, 3
	v_readlane_b32 s68, v255, 4
	v_readlane_b32 s69, v255, 5
	v_readlane_b32 s70, v255, 6
	v_readlane_b32 s71, v255, 7
	v_readlane_b32 s72, v255, 8
	v_readlane_b32 s73, v255, 9
	v_readlane_b32 s74, v255, 10
	v_readlane_b32 s75, v255, 11
	v_readlane_b32 s76, v255, 12
	v_readlane_b32 s77, v255, 13
	v_readlane_b32 s78, v255, 14
	v_readlane_b32 s79, v255, 15
	v_readlane_b32 s80, v255, 16
	v_readlane_b32 s81, v255, 17
	v_readlane_b32 s82, v255, 18
	v_readlane_b32 s83, v255, 19
	v_readlane_b32 s84, v255, 20
	v_readlane_b32 s85, v255, 21
	v_readlane_b32 s86, v255, 22
	v_readlane_b32 s87, v255, 23
	v_readlane_b32 s88, v255, 24
	v_readlane_b32 s89, v255, 25
	v_readlane_b32 s90, v255, 26
	v_readlane_b32 s91, v255, 27
	v_readlane_b32 s92, v255, 28
	v_readlane_b32 s93, v255, 29
	v_readlane_b32 s94, v255, 30
	v_readlane_b32 s95, v255, 31
	v_readlane_b32 s96, v255, 32
	v_readlane_b32 s97, v255, 33
	v_readlane_b32 s98, v255, 34
	v_readlane_b32 s99, v255, 35
	v_readlane_b32 vcc_lo, v255, 36
	v_readlane_b32 vcc_hi, v255, 37
	s_nop 4
